# v014 + SGPR-base LDS-DMA form in the FFN-down K-loop (16 fewer 64-bit VALU adds per iteration)
# speedup vs baseline: 1.0041x; 1.0041x over previous
.Lsp_LBB0353:
	s_add_u32 s36, s0, 0x100
	s_addc_u32 s37, s1, 0
	s_add_i32 s27, 0, 0x10000
	s_cmpk_eq_i32 s26, 0x52
	s_cselect_b32 s69, s65, s37
	s_cselect_b32 s68, s64, s36
	v_add_u32_e32 v144, s27, v146
	s_cselect_b32 s15, s67, s25
	s_cselect_b32 s14, s66, s24
	s_add_i32 s28, 0, 0x14000
	ds_read_b128 v[140:143], v144
	ds_read_b128 v[150:153], v144 offset:1024
	ds_read_b128 v[154:157], v144 offset:2048
	ds_read_b128 v[168:171], v144 offset:3072
	v_add_u32_e32 v144, s28, v146
	ds_read_b128 v[172:175], v144
	ds_read_b128 v[176:179], v144 offset:1024
	ds_read_b128 v[180:183], v144 offset:2048
	ds_read_b128 v[184:187], v144 offset:3072
	s_add_i32 m0, s59, 0xc000
	ds_read_b128 v[188:191], v148
	ds_read_b128 v[192:195], v148 offset:1024
	ds_read_b128 v[196:199], v148 offset:2048
	ds_read_b128 v[200:203], v148 offset:3072
	ds_read_b128 v[204:207], v148 offset:4096
	ds_read_b128 v[216:219], v148 offset:5120
	ds_read_b128 v[220:223], v148 offset:6144
	ds_read_b128 v[224:227], v148 offset:7168
	global_load_lds_dwordx4 v136, s[0:1]
	s_add_i32 m0, s59, 0xe000
	s_nop 0
	global_load_lds_dwordx4 v138, s[0:1]
	s_waitcnt vmcnt(8)
	s_waitcnt lgkmcnt(0)
	s_barrier
	s_waitcnt lgkmcnt(0)
	v_mfma_f32_16x16x32_bf16 v[126:129], v[140:143], v[188:191], v[126:129]
	v_mfma_f32_16x16x32_bf16 v[126:129], v[150:153], v[192:195], v[126:129]
	v_mfma_f32_16x16x32_bf16 v[122:125], v[154:157], v[188:191], v[122:125]
	v_mfma_f32_16x16x32_bf16 v[122:125], v[168:171], v[192:195], v[122:125]
	v_mfma_f32_16x16x32_bf16 v[110:113], v[140:143], v[196:199], v[110:113]
	v_mfma_f32_16x16x32_bf16 v[110:113], v[150:153], v[200:203], v[110:113]
	v_mfma_f32_16x16x32_bf16 v[106:109], v[154:157], v[196:199], v[106:109]
	v_mfma_f32_16x16x32_bf16 v[106:109], v[168:171], v[200:203], v[106:109]
	v_mfma_f32_16x16x32_bf16 v[94:97], v[140:143], v[204:207], v[94:97]
	v_mfma_f32_16x16x32_bf16 v[94:97], v[150:153], v[216:219], v[94:97]
	v_mfma_f32_16x16x32_bf16 v[90:93], v[154:157], v[204:207], v[90:93]
	v_mfma_f32_16x16x32_bf16 v[90:93], v[168:171], v[216:219], v[90:93]
	v_mfma_f32_16x16x32_bf16 v[78:81], v[140:143], v[220:223], v[78:81]
	v_mfma_f32_16x16x32_bf16 v[78:81], v[150:153], v[224:227], v[78:81]
	v_mfma_f32_16x16x32_bf16 v[74:77], v[154:157], v[220:223], v[74:77]
	v_mfma_f32_16x16x32_bf16 v[74:77], v[168:171], v[224:227], v[74:77]
	v_mfma_f32_16x16x32_bf16 v[118:121], v[172:175], v[188:191], v[118:121]
	v_mfma_f32_16x16x32_bf16 v[118:121], v[176:179], v[192:195], v[118:121]
	v_mfma_f32_16x16x32_bf16 v[114:117], v[180:183], v[188:191], v[114:117]
	v_mfma_f32_16x16x32_bf16 v[114:117], v[184:187], v[192:195], v[114:117]
	v_mfma_f32_16x16x32_bf16 v[102:105], v[172:175], v[196:199], v[102:105]
	v_mfma_f32_16x16x32_bf16 v[102:105], v[176:179], v[200:203], v[102:105]
	v_mfma_f32_16x16x32_bf16 v[98:101], v[180:183], v[196:199], v[98:101]
	v_mfma_f32_16x16x32_bf16 v[98:101], v[184:187], v[200:203], v[98:101]
	v_mfma_f32_16x16x32_bf16 v[86:89], v[172:175], v[204:207], v[86:89]
	v_mfma_f32_16x16x32_bf16 v[86:89], v[176:179], v[216:219], v[86:89]
	v_mfma_f32_16x16x32_bf16 v[82:85], v[180:183], v[204:207], v[82:85]
	v_mfma_f32_16x16x32_bf16 v[82:85], v[184:187], v[216:219], v[82:85]
	v_mfma_f32_16x16x32_bf16 v[70:73], v[172:175], v[220:223], v[70:73]
	v_mfma_f32_16x16x32_bf16 v[70:73], v[176:179], v[224:227], v[70:73]
	v_mfma_f32_16x16x32_bf16 v[66:69], v[180:183], v[220:223], v[66:69]
	v_mfma_f32_16x16x32_bf16 v[66:69], v[184:187], v[224:227], v[66:69]
	s_barrier
	s_add_i32 s0, s27, s58
	s_mov_b32 m0, s0
	ds_read_b128 v[188:191], v148 offset:16384
	ds_read_b128 v[192:195], v148 offset:17408
	ds_read_b128 v[196:199], v148 offset:18432
	ds_read_b128 v[200:203], v148 offset:19456
	ds_read_b128 v[204:207], v148 offset:20480
	ds_read_b128 v[216:219], v148 offset:21504
	ds_read_b128 v[220:223], v148 offset:22528
	ds_read_b128 v[224:227], v148 offset:23552
	global_load_lds_dwordx4 v158, s[14:15]
	s_add_i32 m0, s0, 0x2000
	s_add_u32 s0, s14, 0x158000
	s_addc_u32 s1, s15, 0
	s_add_i32 s27, s28, s58
	global_load_lds_dwordx4 v134, s[14:15]
	s_mov_b32 m0, s27
	s_nop 0
	global_load_lds_dwordx4 v158, s[0:1]
	s_add_i32 m0, s27, 0x2000
	s_nop 0
	global_load_lds_dwordx4 v134, s[0:1]
	s_mov_b32 m0, s59
	s_nop 0
	global_load_lds_dwordx4 v130, s[68:69]
	s_mov_b32 m0, s70
	s_nop 0
	global_load_lds_dwordx4 v132, s[68:69]
	s_waitcnt vmcnt(8)
	s_waitcnt lgkmcnt(0)
	s_barrier
	s_waitcnt lgkmcnt(0)
	v_mfma_f32_16x16x32_bf16 v[62:65], v[140:143], v[188:191], v[62:65]
	v_mfma_f32_16x16x32_bf16 v[62:65], v[150:153], v[192:195], v[62:65]
	v_mfma_f32_16x16x32_bf16 v[58:61], v[154:157], v[188:191], v[58:61]
	v_mfma_f32_16x16x32_bf16 v[58:61], v[168:171], v[192:195], v[58:61]
	v_mfma_f32_16x16x32_bf16 v[46:49], v[140:143], v[196:199], v[46:49]
	v_mfma_f32_16x16x32_bf16 v[46:49], v[150:153], v[200:203], v[46:49]
	v_mfma_f32_16x16x32_bf16 v[42:45], v[154:157], v[196:199], v[42:45]
	v_mfma_f32_16x16x32_bf16 v[42:45], v[168:171], v[200:203], v[42:45]
	v_mfma_f32_16x16x32_bf16 v[30:33], v[140:143], v[204:207], v[30:33]
	v_mfma_f32_16x16x32_bf16 v[30:33], v[150:153], v[216:219], v[30:33]
	v_mfma_f32_16x16x32_bf16 v[26:29], v[154:157], v[204:207], v[26:29]
	v_mfma_f32_16x16x32_bf16 v[26:29], v[168:171], v[216:219], v[26:29]
	v_mfma_f32_16x16x32_bf16 v[14:17], v[140:143], v[220:223], v[14:17]
	v_mfma_f32_16x16x32_bf16 v[14:17], v[150:153], v[224:227], v[14:17]
	v_mfma_f32_16x16x32_bf16 v[10:13], v[154:157], v[220:223], v[10:13]
	v_mfma_f32_16x16x32_bf16 v[10:13], v[168:171], v[224:227], v[10:13]
	v_mfma_f32_16x16x32_bf16 v[54:57], v[172:175], v[188:191], v[54:57]
	v_mfma_f32_16x16x32_bf16 v[54:57], v[176:179], v[192:195], v[54:57]
	v_mfma_f32_16x16x32_bf16 v[50:53], v[180:183], v[188:191], v[50:53]
	v_mfma_f32_16x16x32_bf16 v[50:53], v[184:187], v[192:195], v[50:53]
	v_mfma_f32_16x16x32_bf16 v[38:41], v[172:175], v[196:199], v[38:41]
	v_mfma_f32_16x16x32_bf16 v[38:41], v[176:179], v[200:203], v[38:41]
	v_mfma_f32_16x16x32_bf16 v[34:37], v[180:183], v[196:199], v[34:37]
	v_mfma_f32_16x16x32_bf16 v[34:37], v[184:187], v[200:203], v[34:37]
	v_mfma_f32_16x16x32_bf16 v[22:25], v[172:175], v[204:207], v[22:25]
	v_mfma_f32_16x16x32_bf16 v[22:25], v[176:179], v[216:219], v[22:25]
	v_mfma_f32_16x16x32_bf16 v[18:21], v[180:183], v[204:207], v[18:21]
	v_mfma_f32_16x16x32_bf16 v[18:21], v[184:187], v[216:219], v[18:21]
	v_mfma_f32_16x16x32_bf16 v[6:9], v[172:175], v[220:223], v[6:9]
	v_mfma_f32_16x16x32_bf16 v[6:9], v[176:179], v[224:227], v[6:9]
	v_mfma_f32_16x16x32_bf16 v[2:5], v[180:183], v[220:223], v[2:5]
	v_mfma_f32_16x16x32_bf16 v[2:5], v[184:187], v[224:227], v[2:5]
	s_barrier
	s_add_i32 s27, 0, 0x18000
	v_add_u32_e32 v149, s27, v146
	s_add_i32 s28, 0, 0x1c000
	ds_read_b128 v[140:143], v149
	ds_read_b128 v[150:153], v149 offset:1024
	ds_read_b128 v[154:157], v149 offset:2048
	ds_read_b128 v[168:171], v149 offset:3072
	v_add_u32_e32 v149, s28, v146
	ds_read_b128 v[172:175], v149
	ds_read_b128 v[176:179], v149 offset:1024
	ds_read_b128 v[180:183], v149 offset:2048
	ds_read_b128 v[184:187], v149 offset:3072
	s_add_u32 s0, s68, 0x158000
	s_addc_u32 s1, s69, 0
	s_mov_b32 m0, s71
	ds_read_b128 v[188:191], v148 offset:32768
	ds_read_b128 v[192:195], v148 offset:33792
	ds_read_b128 v[196:199], v148 offset:34816
	ds_read_b128 v[200:203], v148 offset:35840
	ds_read_b128 v[204:207], v148 offset:36864
	ds_read_b128 v[216:219], v148 offset:37888
	ds_read_b128 v[220:223], v148 offset:38912
	ds_read_b128 v[224:227], v148 offset:39936
	global_load_lds_dwordx4 v130, s[0:1]
	s_mov_b32 m0, s72
	s_nop 0
	global_load_lds_dwordx4 v132, s[0:1]
	s_waitcnt vmcnt(8)
	s_waitcnt lgkmcnt(0)
	s_barrier
	s_waitcnt lgkmcnt(0)
	v_mfma_f32_16x16x32_bf16 v[126:129], v[140:143], v[188:191], v[126:129]
	v_mfma_f32_16x16x32_bf16 v[126:129], v[150:153], v[192:195], v[126:129]
	v_mfma_f32_16x16x32_bf16 v[122:125], v[154:157], v[188:191], v[122:125]
	v_mfma_f32_16x16x32_bf16 v[122:125], v[168:171], v[192:195], v[122:125]
	v_mfma_f32_16x16x32_bf16 v[110:113], v[140:143], v[196:199], v[110:113]
	v_mfma_f32_16x16x32_bf16 v[110:113], v[150:153], v[200:203], v[110:113]
	v_mfma_f32_16x16x32_bf16 v[106:109], v[154:157], v[196:199], v[106:109]
	v_mfma_f32_16x16x32_bf16 v[106:109], v[168:171], v[200:203], v[106:109]
	v_mfma_f32_16x16x32_bf16 v[94:97], v[140:143], v[204:207], v[94:97]
	v_mfma_f32_16x16x32_bf16 v[94:97], v[150:153], v[216:219], v[94:97]
	v_mfma_f32_16x16x32_bf16 v[90:93], v[154:157], v[204:207], v[90:93]
	v_mfma_f32_16x16x32_bf16 v[90:93], v[168:171], v[216:219], v[90:93]
	v_mfma_f32_16x16x32_bf16 v[78:81], v[140:143], v[220:223], v[78:81]
	v_mfma_f32_16x16x32_bf16 v[78:81], v[150:153], v[224:227], v[78:81]
	v_mfma_f32_16x16x32_bf16 v[74:77], v[154:157], v[220:223], v[74:77]
	v_mfma_f32_16x16x32_bf16 v[74:77], v[168:171], v[224:227], v[74:77]
	v_mfma_f32_16x16x32_bf16 v[118:121], v[172:175], v[188:191], v[118:121]
	v_mfma_f32_16x16x32_bf16 v[118:121], v[176:179], v[192:195], v[118:121]
	v_mfma_f32_16x16x32_bf16 v[114:117], v[180:183], v[188:191], v[114:117]
	v_mfma_f32_16x16x32_bf16 v[114:117], v[184:187], v[192:195], v[114:117]
	v_mfma_f32_16x16x32_bf16 v[102:105], v[172:175], v[196:199], v[102:105]
	v_mfma_f32_16x16x32_bf16 v[102:105], v[176:179], v[200:203], v[102:105]
	v_mfma_f32_16x16x32_bf16 v[98:101], v[180:183], v[196:199], v[98:101]
	v_mfma_f32_16x16x32_bf16 v[98:101], v[184:187], v[200:203], v[98:101]
	v_mfma_f32_16x16x32_bf16 v[86:89], v[172:175], v[204:207], v[86:89]
	v_mfma_f32_16x16x32_bf16 v[86:89], v[176:179], v[216:219], v[86:89]
	v_mfma_f32_16x16x32_bf16 v[82:85], v[180:183], v[204:207], v[82:85]
	v_mfma_f32_16x16x32_bf16 v[82:85], v[184:187], v[216:219], v[82:85]
	v_mfma_f32_16x16x32_bf16 v[70:73], v[172:175], v[220:223], v[70:73]
	v_mfma_f32_16x16x32_bf16 v[70:73], v[176:179], v[224:227], v[70:73]
	v_mfma_f32_16x16x32_bf16 v[66:69], v[180:183], v[220:223], v[66:69]
	v_mfma_f32_16x16x32_bf16 v[66:69], v[184:187], v[224:227], v[66:69]
	s_barrier
	s_add_i32 s0, s27, s58
	s_add_u32 s100, s14, 0x80
	s_addc_u32 s101, s15, 0
	s_mov_b32 m0, s0
	ds_read_b128 v[188:191], v148 offset:49152
	ds_read_b128 v[192:195], v148 offset:50176
	ds_read_b128 v[196:199], v148 offset:51200
	ds_read_b128 v[200:203], v148 offset:52224
	ds_read_b128 v[204:207], v148 offset:53248
	ds_read_b128 v[216:219], v148 offset:54272
	ds_read_b128 v[220:223], v148 offset:55296
	ds_read_b128 v[224:227], v148 offset:56320
	global_load_lds_dwordx4 v158, s[100:101]
	s_add_i32 m0, s0, 0x2000
	s_add_u32 s0, s14, 0x158080
	s_addc_u32 s1, s15, 0
	s_add_i32 s14, s28, s58
	global_load_lds_dwordx4 v134, s[100:101]
	s_add_u32 s100, s68, 0x80
	s_addc_u32 s101, s69, 0
	s_mov_b32 m0, s14
	s_nop 0
	global_load_lds_dwordx4 v158, s[0:1]
	s_add_i32 m0, s14, 0x2000
	s_nop 0
	global_load_lds_dwordx4 v134, s[0:1]
	s_mov_b32 m0, s73
	s_nop 0
	global_load_lds_dwordx4 v130, s[100:101]
	s_mov_b32 m0, s74
	s_nop 0
	global_load_lds_dwordx4 v132, s[100:101]
	s_waitcnt vmcnt(8)
	s_waitcnt lgkmcnt(0)
	s_barrier
	s_waitcnt lgkmcnt(0)
	v_mfma_f32_16x16x32_bf16 v[62:65], v[140:143], v[188:191], v[62:65]
	v_mfma_f32_16x16x32_bf16 v[62:65], v[150:153], v[192:195], v[62:65]
	v_mfma_f32_16x16x32_bf16 v[58:61], v[154:157], v[188:191], v[58:61]
	v_mfma_f32_16x16x32_bf16 v[58:61], v[168:171], v[192:195], v[58:61]
	v_mfma_f32_16x16x32_bf16 v[46:49], v[140:143], v[196:199], v[46:49]
	v_mfma_f32_16x16x32_bf16 v[46:49], v[150:153], v[200:203], v[46:49]
	v_mfma_f32_16x16x32_bf16 v[42:45], v[154:157], v[196:199], v[42:45]
	v_mfma_f32_16x16x32_bf16 v[42:45], v[168:171], v[200:203], v[42:45]
	v_mfma_f32_16x16x32_bf16 v[30:33], v[140:143], v[204:207], v[30:33]
	v_mfma_f32_16x16x32_bf16 v[30:33], v[150:153], v[216:219], v[30:33]
	v_mfma_f32_16x16x32_bf16 v[26:29], v[154:157], v[204:207], v[26:29]
	v_mfma_f32_16x16x32_bf16 v[26:29], v[168:171], v[216:219], v[26:29]
	v_mfma_f32_16x16x32_bf16 v[14:17], v[140:143], v[220:223], v[14:17]
	v_mfma_f32_16x16x32_bf16 v[14:17], v[150:153], v[224:227], v[14:17]
	v_mfma_f32_16x16x32_bf16 v[10:13], v[154:157], v[220:223], v[10:13]
	v_mfma_f32_16x16x32_bf16 v[10:13], v[168:171], v[224:227], v[10:13]
	v_mfma_f32_16x16x32_bf16 v[54:57], v[172:175], v[188:191], v[54:57]
	v_mfma_f32_16x16x32_bf16 v[54:57], v[176:179], v[192:195], v[54:57]
	v_mfma_f32_16x16x32_bf16 v[50:53], v[180:183], v[188:191], v[50:53]
	v_mfma_f32_16x16x32_bf16 v[50:53], v[184:187], v[192:195], v[50:53]
	v_mfma_f32_16x16x32_bf16 v[38:41], v[172:175], v[196:199], v[38:41]
	v_mfma_f32_16x16x32_bf16 v[38:41], v[176:179], v[200:203], v[38:41]
	v_mfma_f32_16x16x32_bf16 v[34:37], v[180:183], v[196:199], v[34:37]
	v_mfma_f32_16x16x32_bf16 v[34:37], v[184:187], v[200:203], v[34:37]
	v_mfma_f32_16x16x32_bf16 v[22:25], v[172:175], v[204:207], v[22:25]
	v_mfma_f32_16x16x32_bf16 v[22:25], v[176:179], v[216:219], v[22:25]
	v_mfma_f32_16x16x32_bf16 v[18:21], v[180:183], v[204:207], v[18:21]
	v_mfma_f32_16x16x32_bf16 v[18:21], v[184:187], v[216:219], v[18:21]
	v_mfma_f32_16x16x32_bf16 v[6:9], v[172:175], v[220:223], v[6:9]
	v_mfma_f32_16x16x32_bf16 v[6:9], v[176:179], v[224:227], v[6:9]
	v_mfma_f32_16x16x32_bf16 v[2:5], v[180:183], v[220:223], v[2:5]
	v_mfma_f32_16x16x32_bf16 v[2:5], v[184:187], v[224:227], v[2:5]
	s_barrier
	s_add_i32 s26, s26, 2
	s_add_u32 s24, s24, 0x100
	s_addc_u32 s25, s25, 0
	s_cmpk_gt_u32 s26, 0x53
	s_mov_b64 s[0:1], s[36:37]
	s_cbranch_scc0 .LBB0_353
	s_and_b64 vcc, exec, s[12:13]
	s_cbranch_vccz .LBB0_356
	s_barrier

	.amdhsa_kernel _Z6mk_fwd4Args
		.amdhsa_group_segment_fixed_size 0
		.amdhsa_private_segment_fixed_size 0
		.amdhsa_kernarg_size 560
		.amdhsa_user_sgpr_count 2
		.amdhsa_user_sgpr_dispatch_ptr 0
		.amdhsa_user_sgpr_queue_ptr 0
		.amdhsa_user_sgpr_kernarg_segment_ptr 1
		.amdhsa_user_sgpr_dispatch_id 0
		.amdhsa_user_sgpr_kernarg_preload_length 0
		.amdhsa_user_sgpr_kernarg_preload_offset 0
		.amdhsa_user_sgpr_private_segment_size 0
		.amdhsa_uses_dynamic_stack 0
		.amdhsa_enable_private_segment 0
		.amdhsa_system_sgpr_workgroup_id_x 1
		.amdhsa_system_sgpr_workgroup_id_y 0
		.amdhsa_system_sgpr_workgroup_id_z 0
		.amdhsa_system_sgpr_workgroup_info 0
		.amdhsa_system_vgpr_workitem_id 0
		.amdhsa_next_free_vgpr 245
		.amdhsa_next_free_sgpr 102
		.amdhsa_accum_offset 248
		.amdhsa_reserve_vcc 1
		.amdhsa_float_round_mode_32 0
		.amdhsa_float_round_mode_16_64 0
		.amdhsa_float_denorm_mode_32 3
		.amdhsa_float_denorm_mode_16_64 3
		.amdhsa_dx10_clamp 1
		.amdhsa_ieee_mode 1
		.amdhsa_fp16_overflow 0
		.amdhsa_tg_split 0
		.amdhsa_exception_fp_ieee_invalid_op 0
		.amdhsa_exception_fp_denorm_src 0
		.amdhsa_exception_fp_ieee_div_zero 0
		.amdhsa_exception_fp_ieee_overflow 0
		.amdhsa_exception_fp_ieee_underflow 0
		.amdhsa_exception_fp_ieee_inexact 0
		.amdhsa_exception_int_div_zero 0
	.end_amdhsa_kernel

amdhsa.kernels:
  - .agpr_count:     0
    .args:
      - .offset:         0
        .size:           304
        .value_kind:     by_value
      - .offset:         304
        .size:           4
        .value_kind:     hidden_block_count_x
      - .offset:         308
        .size:           4
        .value_kind:     hidden_block_count_y
      - .offset:         312
        .size:           4
        .value_kind:     hidden_block_count_z
      - .offset:         316
        .size:           2
        .value_kind:     hidden_group_size_x
      - .offset:         318
        .size:           2
        .value_kind:     hidden_group_size_y
      - .offset:         320
        .size:           2
        .value_kind:     hidden_group_size_z
      - .offset:         322
        .size:           2
        .value_kind:     hidden_remainder_x
      - .offset:         324
        .size:           2
        .value_kind:     hidden_remainder_y
      - .offset:         326
        .size:           2
        .value_kind:     hidden_remainder_z
      - .offset:         344
        .size:           8
        .value_kind:     hidden_global_offset_x
      - .offset:         352
        .size:           8
        .value_kind:     hidden_global_offset_y
      - .offset:         360
        .size:           8
        .value_kind:     hidden_global_offset_z
      - .offset:         368
        .size:           2
        .value_kind:     hidden_grid_dims
      - .offset:         424
        .size:           4
        .value_kind:     hidden_dynamic_lds_size
    .group_segment_fixed_size: 0
    .kernarg_segment_align: 8
    .kernarg_segment_size: 560
    .language:       OpenCL C
    .language_version:
      - 2
      - 0
    .max_flat_workgroup_size: 512
    .name:           _Z6mk_fwd4Args
    .private_segment_fixed_size: 0
    .sgpr_count:     108
    .sgpr_spill_count: 303
    .symbol:         _Z6mk_fwd4Args.kd
    .uniform_work_group_size: 1
    .uses_dynamic_stack: false
    .vgpr_count:     245
    .vgpr_spill_count: 0
    .wavefront_size: 64
